# weight conversion tile order: adjacent waves take k-adjacent tiles so both 64-B halves of each destination line are written together (full-line write-back)
# speedup vs baseline: 1.0293x; 1.0057x over previous
.Lwt_loop:
	s_cmp_gt_i32 s66, s98
	s_cbranch_scc1 .Lwt_done
	s_lshl_b32 s67, s99, 1
	s_add_i32 s67, s67, s66
	s_cmp_gt_i32 s67, s98
	s_cbranch_scc1 .Lwt_single
	s_cmpk_ge_i32 s66, 0xc00
	s_cselect_b32 s0, 1, 0
	s_mul_i32 s1, s0, 0xc00
	s_sub_i32 s1, s66, s1
	s_mul_i32 s4, s0, 0x1800000
	s_add_u32 s70, s64, s4
	s_addc_u32 s71, s65, 0
	s_lshl_b32 s69, s0, 12
	s_cmpk_lt_i32 s1, 0x300
	s_cbranch_scc1 .Lwt_in_1
	s_cmpk_lt_i32 s1, 0x400
	s_cbranch_scc1 .Lwt_out_1
	s_cmpk_lt_i32 s1, 0x800
	s_cbranch_scc1 .Lwt_up_1
	s_sub_i32 s1, s1, 0x800
	s_and_b32 s75, s1, 1
	s_lshr_b32 s1, s1, 1
	s_lshr_b32 s72, s1, 3
	s_and_b32 s73, s1, 7
	s_lshl_b32 s72, s72, 1
	s_or_b32 s72, s72, s75
	s_movk_i32 s74, 0x400
	s_mul_i32 s4, s0, 0x1000000
	s_add_u32 s76, s18, s4
	s_addc_u32 s77, s19, 0
	s_mov_b32 s4, 0x1000000
	s_lshl_b32 s5, s73, 7
	s_movk_i32 s27, 0xd00
	s_branch .Lwt_join_1
.Lwt_in_1:
	s_and_b32 s75, s1, 1
	s_lshr_b32 s1, s1, 1
	s_mul_i32 s72, s1, 0xaab
	s_lshr_b32 s72, s72, 16
	s_mul_i32 s73, s72, 24
	s_sub_i32 s73, s1, s73
	s_lshl_b32 s72, s72, 1
	s_or_b32 s72, s72, s75
	s_movk_i32 s74, 0xc00
	s_mul_i32 s4, s0, 0xc00000
	s_add_u32 s76, s8, s4
	s_addc_u32 s77, s9, 0
	s_add_u32 s24, s10, s69
	s_addc_u32 s25, s11, 0
	s_mov_b32 s4, 0
	s_movk_i32 s27, 0xb01
	s_cmpk_lt_u32 s73, 8
	s_cbranch_scc0 .Lwt_in_b_1
	s_and_b32 s5, s73, 3
	s_lshl_b32 s5, s5, 8
	s_lshr_b32 s75, s73, 2
	s_lshl_b32 s75, s75, 7
	s_add_i32 s5, s5, s75
	s_branch .Lwt_join_1

.Lwt_out_1:
	s_sub_i32 s1, s1, 0x300
	s_and_b32 s75, s1, 1
	s_lshr_b32 s1, s1, 1
	s_lshr_b32 s72, s1, 3
	s_and_b32 s73, s1, 7
	s_lshl_b32 s72, s72, 1
	s_or_b32 s72, s72, s75
	s_movk_i32 s74, 0x400
	s_mul_i32 s4, s0, 0x400000
	s_add_u32 s76, s12, s4
	s_addc_u32 s77, s13, 0
	s_mov_b32 s4, 0x600000
	s_lshl_b32 s5, s73, 7
	s_movk_i32 s27, 0xb00
	s_branch .Lwt_join_1
.Lwt_up_1:
	s_sub_i32 s1, s1, 0x400
	s_and_b32 s75, s1, 1
	s_lshr_b32 s1, s1, 1
	s_lshr_b32 s72, s1, 5
	s_and_b32 s73, s1, 31
	s_lshl_b32 s72, s72, 1
	s_or_b32 s72, s72, s75
	s_movk_i32 s74, 0x1000
	s_mul_i32 s4, s0, 0x1000000
	s_add_u32 s76, s16, s4
	s_addc_u32 s77, s17, 0
	s_add_u32 s24, s14, s69
	s_addc_u32 s25, s15, 0
	s_mov_b32 s4, 0x800000
	s_lshl_b32 s5, s73, 7
	s_movk_i32 s27, 0xb01
.Lwt_join_1:
	s_mul_i32 s0, s72, s74
	s_lshl_b32 s0, s0, 5
	s_lshl_b32 s1, s73, 7
	s_add_i32 s0, s0, s1
	s_lshl_b32 s0, s0, 2
	s_add_u32 s20, s76, s0
	s_addc_u32 s21, s77, 0
	s_lshl_b32 s26, s74, 2
	s_lshr_b32 s0, s27, 8
	s_lshl_b32 s0, s5, s0
	s_add_i32 s0, s0, s4
	s_lshl_b32 s1, s72, 6
	s_add_i32 s0, s0, s1
	s_add_u32 s22, s70, s0
	s_addc_u32 s23, s71, 0
	s_lshl_b32 s1, s72, 7
	s_add_u32 s24, s24, s1
	s_addc_u32 s25, s25, 0
	s_lshl_b32 s0, s26, 4
	v_mad_u32_u24 v217, v213, s0, v212
	global_load_dwordx4 v[4:7], v217, s[20:21] nt
	s_add_u32 s20, s20, s26
	s_addc_u32 s21, s21, 0
	global_load_dwordx4 v[8:11], v217, s[20:21] nt
	s_add_u32 s20, s20, s26
	s_addc_u32 s21, s21, 0
	global_load_dwordx4 v[12:15], v217, s[20:21] nt
	s_add_u32 s20, s20, s26
	s_addc_u32 s21, s21, 0
	global_load_dwordx4 v[16:19], v217, s[20:21] nt
	s_add_u32 s20, s20, s26
	s_addc_u32 s21, s21, 0
	global_load_dwordx4 v[20:23], v217, s[20:21] nt
	s_add_u32 s20, s20, s26
	s_addc_u32 s21, s21, 0
	global_load_dwordx4 v[24:27], v217, s[20:21] nt
	s_add_u32 s20, s20, s26
	s_addc_u32 s21, s21, 0
	global_load_dwordx4 v[28:31], v217, s[20:21] nt
	s_add_u32 s20, s20, s26
	s_addc_u32 s21, s21, 0
	global_load_dwordx4 v[32:35], v217, s[20:21] nt
	s_add_u32 s20, s20, s26
	s_addc_u32 s21, s21, 0
	global_load_dwordx4 v[36:39], v217, s[20:21] nt
	s_add_u32 s20, s20, s26
	s_addc_u32 s21, s21, 0
	global_load_dwordx4 v[40:43], v217, s[20:21] nt
	s_add_u32 s20, s20, s26
	s_addc_u32 s21, s21, 0
	global_load_dwordx4 v[44:47], v217, s[20:21] nt
	s_add_u32 s20, s20, s26
	s_addc_u32 s21, s21, 0
	global_load_dwordx4 v[48:51], v217, s[20:21] nt
	s_add_u32 s20, s20, s26
	s_addc_u32 s21, s21, 0
	global_load_dwordx4 v[52:55], v217, s[20:21] nt
	s_add_u32 s20, s20, s26
	s_addc_u32 s21, s21, 0
	global_load_dwordx4 v[56:59], v217, s[20:21] nt
	s_add_u32 s20, s20, s26
	s_addc_u32 s21, s21, 0
	global_load_dwordx4 v[60:63], v217, s[20:21] nt
	s_add_u32 s20, s20, s26
	s_addc_u32 s21, s21, 0
	global_load_dwordx4 v[64:67], v217, s[20:21] nt
	s_add_i32 s68, s66, s99
	s_cmpk_ge_i32 s68, 0xc00
	s_cselect_b32 s0, 1, 0
	s_mul_i32 s1, s0, 0xc00
	s_sub_i32 s1, s68, s1
	s_mul_i32 s4, s0, 0x1800000
	s_add_u32 s70, s64, s4
	s_addc_u32 s71, s65, 0
	s_lshl_b32 s69, s0, 12
	s_cmpk_lt_i32 s1, 0x300
	s_cbranch_scc1 .Lwt_in_2
	s_cmpk_lt_i32 s1, 0x400
	s_cbranch_scc1 .Lwt_out_2
	s_cmpk_lt_i32 s1, 0x800
	s_cbranch_scc1 .Lwt_up_2
	s_sub_i32 s1, s1, 0x800
	s_and_b32 s75, s1, 1
	s_lshr_b32 s1, s1, 1
	s_lshr_b32 s72, s1, 3
	s_and_b32 s73, s1, 7
	s_lshl_b32 s72, s72, 1
	s_or_b32 s72, s72, s75
	s_movk_i32 s74, 0x400
	s_mul_i32 s4, s0, 0x1000000
	s_add_u32 s76, s18, s4
	s_addc_u32 s77, s19, 0
	s_mov_b32 s4, 0x1000000
	s_lshl_b32 s5, s73, 7
	s_movk_i32 s35, 0xd00
	s_branch .Lwt_join_2
.Lwt_in_2:
	s_and_b32 s75, s1, 1
	s_lshr_b32 s1, s1, 1
	s_mul_i32 s72, s1, 0xaab
	s_lshr_b32 s72, s72, 16
	s_mul_i32 s73, s72, 24
	s_sub_i32 s73, s1, s73
	s_lshl_b32 s72, s72, 1
	s_or_b32 s72, s72, s75
	s_movk_i32 s74, 0xc00
	s_mul_i32 s4, s0, 0xc00000
	s_add_u32 s76, s8, s4
	s_addc_u32 s77, s9, 0
	s_add_u32 s32, s10, s69
	s_addc_u32 s33, s11, 0
	s_mov_b32 s4, 0
	s_movk_i32 s35, 0xb01
	s_cmpk_lt_u32 s73, 8
	s_cbranch_scc0 .Lwt_in_b_2
	s_and_b32 s5, s73, 3
	s_lshl_b32 s5, s5, 8
	s_lshr_b32 s75, s73, 2
	s_lshl_b32 s75, s75, 7
	s_add_i32 s5, s5, s75
	s_branch .Lwt_join_2

.Lwt_out_2:
	s_sub_i32 s1, s1, 0x300
	s_and_b32 s75, s1, 1
	s_lshr_b32 s1, s1, 1
	s_lshr_b32 s72, s1, 3
	s_and_b32 s73, s1, 7
	s_lshl_b32 s72, s72, 1
	s_or_b32 s72, s72, s75
	s_movk_i32 s74, 0x400
	s_mul_i32 s4, s0, 0x400000
	s_add_u32 s76, s12, s4
	s_addc_u32 s77, s13, 0
	s_mov_b32 s4, 0x600000
	s_lshl_b32 s5, s73, 7
	s_movk_i32 s35, 0xb00
	s_branch .Lwt_join_2
.Lwt_up_2:
	s_sub_i32 s1, s1, 0x400
	s_and_b32 s75, s1, 1
	s_lshr_b32 s1, s1, 1
	s_lshr_b32 s72, s1, 5
	s_and_b32 s73, s1, 31
	s_lshl_b32 s72, s72, 1
	s_or_b32 s72, s72, s75
	s_movk_i32 s74, 0x1000
	s_mul_i32 s4, s0, 0x1000000
	s_add_u32 s76, s16, s4
	s_addc_u32 s77, s17, 0
	s_add_u32 s32, s14, s69
	s_addc_u32 s33, s15, 0
	s_mov_b32 s4, 0x800000
	s_lshl_b32 s5, s73, 7
	s_movk_i32 s35, 0xb01
.Lwt_join_2:
	s_mul_i32 s0, s72, s74
	s_lshl_b32 s0, s0, 5
	s_lshl_b32 s1, s73, 7
	s_add_i32 s0, s0, s1
	s_lshl_b32 s0, s0, 2
	s_add_u32 s28, s76, s0
	s_addc_u32 s29, s77, 0
	s_lshl_b32 s34, s74, 2
	s_lshr_b32 s0, s35, 8
	s_lshl_b32 s0, s5, s0
	s_add_i32 s0, s0, s4
	s_lshl_b32 s1, s72, 6
	s_add_i32 s0, s0, s1
	s_add_u32 s30, s70, s0
	s_addc_u32 s31, s71, 0
	s_lshl_b32 s1, s72, 7
	s_add_u32 s32, s32, s1
	s_addc_u32 s33, s33, 0
	s_lshl_b32 s0, s34, 4
	v_mad_u32_u24 v217, v213, s0, v212
	global_load_dwordx4 v[68:71], v217, s[28:29] nt
	s_add_u32 s28, s28, s34
	s_addc_u32 s29, s29, 0
	global_load_dwordx4 v[72:75], v217, s[28:29] nt
	s_add_u32 s28, s28, s34
	s_addc_u32 s29, s29, 0
	global_load_dwordx4 v[76:79], v217, s[28:29] nt
	s_add_u32 s28, s28, s34
	s_addc_u32 s29, s29, 0
	global_load_dwordx4 v[80:83], v217, s[28:29] nt
	s_add_u32 s28, s28, s34
	s_addc_u32 s29, s29, 0
	global_load_dwordx4 v[84:87], v217, s[28:29] nt
	s_add_u32 s28, s28, s34
	s_addc_u32 s29, s29, 0
	global_load_dwordx4 v[88:91], v217, s[28:29] nt
	s_add_u32 s28, s28, s34
	s_addc_u32 s29, s29, 0
	global_load_dwordx4 v[92:95], v217, s[28:29] nt
	s_add_u32 s28, s28, s34
	s_addc_u32 s29, s29, 0
	global_load_dwordx4 v[96:99], v217, s[28:29] nt
	s_add_u32 s28, s28, s34
	s_addc_u32 s29, s29, 0
	global_load_dwordx4 v[100:103], v217, s[28:29] nt
	s_add_u32 s28, s28, s34
	s_addc_u32 s29, s29, 0
	global_load_dwordx4 v[104:107], v217, s[28:29] nt
	s_add_u32 s28, s28, s34
	s_addc_u32 s29, s29, 0
	global_load_dwordx4 v[108:111], v217, s[28:29] nt
	s_add_u32 s28, s28, s34
	s_addc_u32 s29, s29, 0
	global_load_dwordx4 v[112:115], v217, s[28:29] nt
	s_add_u32 s28, s28, s34
	s_addc_u32 s29, s29, 0
	global_load_dwordx4 v[116:119], v217, s[28:29] nt
	s_add_u32 s28, s28, s34
	s_addc_u32 s29, s29, 0
	global_load_dwordx4 v[120:123], v217, s[28:29] nt
	s_add_u32 s28, s28, s34
	s_addc_u32 s29, s29, 0
	global_load_dwordx4 v[124:127], v217, s[28:29] nt
	s_add_u32 s28, s28, s34
	s_addc_u32 s29, s29, 0
	global_load_dwordx4 v[128:131], v217, s[28:29] nt
	s_cmpk_ge_i32 s67, 0xc00
	s_cselect_b32 s0, 1, 0
	s_mul_i32 s1, s0, 0xc00
	s_sub_i32 s1, s67, s1
	s_mul_i32 s4, s0, 0x1800000
	s_add_u32 s70, s64, s4
	s_addc_u32 s71, s65, 0
	s_lshl_b32 s69, s0, 12
	s_cmpk_lt_i32 s1, 0x300
	s_cbranch_scc1 .Lwt_in_3
	s_cmpk_lt_i32 s1, 0x400
	s_cbranch_scc1 .Lwt_out_3
	s_cmpk_lt_i32 s1, 0x800
	s_cbranch_scc1 .Lwt_up_3
	s_sub_i32 s1, s1, 0x800
	s_and_b32 s75, s1, 1
	s_lshr_b32 s1, s1, 1
	s_lshr_b32 s72, s1, 3
	s_and_b32 s73, s1, 7
	s_lshl_b32 s72, s72, 1
	s_or_b32 s72, s72, s75
	s_movk_i32 s74, 0x400
	s_mul_i32 s4, s0, 0x1000000
	s_add_u32 s76, s18, s4
	s_addc_u32 s77, s19, 0
	s_mov_b32 s4, 0x1000000
	s_lshl_b32 s5, s73, 7
	s_movk_i32 s47, 0xd00
	s_branch .Lwt_join_3
.Lwt_in_3:
	s_and_b32 s75, s1, 1
	s_lshr_b32 s1, s1, 1
	s_mul_i32 s72, s1, 0xaab
	s_lshr_b32 s72, s72, 16
	s_mul_i32 s73, s72, 24
	s_sub_i32 s73, s1, s73
	s_lshl_b32 s72, s72, 1
	s_or_b32 s72, s72, s75
	s_movk_i32 s74, 0xc00
	s_mul_i32 s4, s0, 0xc00000
	s_add_u32 s76, s8, s4
	s_addc_u32 s77, s9, 0
	s_add_u32 s44, s10, s69
	s_addc_u32 s45, s11, 0
	s_mov_b32 s4, 0
	s_movk_i32 s47, 0xb01
	s_cmpk_lt_u32 s73, 8
	s_cbranch_scc0 .Lwt_in_b_3
	s_and_b32 s5, s73, 3
	s_lshl_b32 s5, s5, 8
	s_lshr_b32 s75, s73, 2
	s_lshl_b32 s75, s75, 7
	s_add_i32 s5, s5, s75
	s_branch .Lwt_join_3

.Lwt_out_3:
	s_sub_i32 s1, s1, 0x300
	s_and_b32 s75, s1, 1
	s_lshr_b32 s1, s1, 1
	s_lshr_b32 s72, s1, 3
	s_and_b32 s73, s1, 7
	s_lshl_b32 s72, s72, 1
	s_or_b32 s72, s72, s75
	s_movk_i32 s74, 0x400
	s_mul_i32 s4, s0, 0x400000
	s_add_u32 s76, s12, s4
	s_addc_u32 s77, s13, 0
	s_mov_b32 s4, 0x600000
	s_lshl_b32 s5, s73, 7
	s_movk_i32 s47, 0xb00
	s_branch .Lwt_join_3
.Lwt_up_3:
	s_sub_i32 s1, s1, 0x400
	s_and_b32 s75, s1, 1
	s_lshr_b32 s1, s1, 1
	s_lshr_b32 s72, s1, 5
	s_and_b32 s73, s1, 31
	s_lshl_b32 s72, s72, 1
	s_or_b32 s72, s72, s75
	s_movk_i32 s74, 0x1000
	s_mul_i32 s4, s0, 0x1000000
	s_add_u32 s76, s16, s4
	s_addc_u32 s77, s17, 0
	s_add_u32 s44, s14, s69
	s_addc_u32 s45, s15, 0
	s_mov_b32 s4, 0x800000
	s_lshl_b32 s5, s73, 7
	s_movk_i32 s47, 0xb01

.Lwt_single:
	s_cmpk_ge_i32 s66, 0xc00
	s_cselect_b32 s0, 1, 0
	s_mul_i32 s1, s0, 0xc00
	s_sub_i32 s1, s66, s1
	s_mul_i32 s4, s0, 0x1800000
	s_add_u32 s70, s64, s4
	s_addc_u32 s71, s65, 0
	s_lshl_b32 s69, s0, 12
	s_cmpk_lt_i32 s1, 0x300
	s_cbranch_scc1 .Lwt_in_7
	s_cmpk_lt_i32 s1, 0x400
	s_cbranch_scc1 .Lwt_out_7
	s_cmpk_lt_i32 s1, 0x800
	s_cbranch_scc1 .Lwt_up_7
	s_sub_i32 s1, s1, 0x800
	s_and_b32 s75, s1, 1
	s_lshr_b32 s1, s1, 1
	s_lshr_b32 s72, s1, 3
	s_and_b32 s73, s1, 7
	s_lshl_b32 s72, s72, 1
	s_or_b32 s72, s72, s75
	s_movk_i32 s74, 0x400
	s_mul_i32 s4, s0, 0x1000000
	s_add_u32 s76, s18, s4
	s_addc_u32 s77, s19, 0
	s_mov_b32 s4, 0x1000000
	s_lshl_b32 s5, s73, 7
	s_movk_i32 s27, 0xd00
	s_branch .Lwt_join_7

.LBB0_441:
	s_or_b64 exec, exec, s[40:41]
	s_xor_b64 s[0:1], s[62:63], -1
	v_writelane_b32 v252, s0, 48
	s_mov_b32 s37, s93
	s_andn2_b64 vcc, exec, s[66:67]
	v_writelane_b32 v252, s1, 49
	s_waitcnt lgkmcnt(0)
	s_barrier
	s_cbranch_vccnz .LBB0_531
	v_readlane_b32 s98, v252, 47
	s_cmp_lg_u32 s98, 0
	s_cbranch_scc1 .Lw1_skip
	s_cmpk_lg_u32 s78, 0x100
	s_cbranch_scc1 .Lw1_skip
	s_cmpk_lt_u32 s2, 0x80
	s_cbranch_scc1 .Lw1_skip
	v_writelane_b32 v254, s8, 0
	v_writelane_b32 v254, s9, 1
	v_writelane_b32 v254, s10, 2
	v_writelane_b32 v254, s11, 3
	v_writelane_b32 v254, s12, 4
	v_writelane_b32 v254, s13, 5
	v_writelane_b32 v254, s14, 6
	v_writelane_b32 v254, s15, 7
	v_writelane_b32 v254, s16, 8
	v_writelane_b32 v254, s17, 9
	v_writelane_b32 v254, s18, 10
	v_writelane_b32 v254, s19, 11
	v_writelane_b32 v254, s20, 12
	v_writelane_b32 v254, s21, 13
	v_writelane_b32 v254, s22, 14
	v_writelane_b32 v254, s23, 15
	v_writelane_b32 v254, s24, 16
	v_writelane_b32 v254, s25, 17
	v_writelane_b32 v254, s26, 18
	v_writelane_b32 v254, s27, 19
	v_writelane_b32 v254, s28, 20
	v_writelane_b32 v254, s29, 21
	v_writelane_b32 v254, s30, 22
	v_writelane_b32 v254, s31, 23
	v_writelane_b32 v254, s32, 24
	v_writelane_b32 v254, s33, 25
	v_writelane_b32 v254, s34, 26
	v_writelane_b32 v254, s35, 27
	v_writelane_b32 v254, s40, 28
	v_writelane_b32 v254, s41, 29
	v_writelane_b32 v254, s42, 30
	v_writelane_b32 v254, s43, 31
	v_writelane_b32 v254, s44, 32
	v_writelane_b32 v254, s45, 33
	v_writelane_b32 v254, s46, 34
	v_writelane_b32 v254, s47, 35
	v_writelane_b32 v254, s48, 36
	v_writelane_b32 v254, s49, 37
	v_writelane_b32 v254, s50, 38
	v_writelane_b32 v254, s51, 39
	v_writelane_b32 v254, s52, 40
	v_writelane_b32 v254, s53, 41
	v_writelane_b32 v254, s54, 42
	v_writelane_b32 v254, s55, 43
	v_writelane_b32 v254, s56, 44
	v_writelane_b32 v254, s57, 45
	v_writelane_b32 v254, s58, 46
	v_writelane_b32 v254, s59, 47
	v_writelane_b32 v254, s60, 48
	v_writelane_b32 v254, s61, 49
	v_writelane_b32 v254, s62, 50
	v_writelane_b32 v254, s63, 51
	v_writelane_b32 v254, s66, 52
	v_writelane_b32 v254, s67, 53
	v_writelane_b32 v254, s68, 54
	v_writelane_b32 v254, s69, 55
	v_writelane_b32 v254, s70, 56
	v_writelane_b32 v254, s71, 57
	v_writelane_b32 v254, s72, 58
	v_writelane_b32 v254, s73, 59
	v_writelane_b32 v254, s74, 60
	v_writelane_b32 v254, s75, 61
	v_writelane_b32 v254, s76, 62
	v_writelane_b32 v254, s77, 63
	v_writelane_b32 v255, s80, 0
	v_writelane_b32 v255, s81, 1
	v_writelane_b32 v255, s82, 2
	v_writelane_b32 v255, s83, 3
	v_writelane_b32 v255, s84, 4
	v_writelane_b32 v255, s85, 5
	v_writelane_b32 v255, s86, 6
	v_writelane_b32 v255, s87, 7
	v_writelane_b32 v255, s88, 8
	v_writelane_b32 v255, s89, 9
	v_writelane_b32 v255, s90, 10
	v_writelane_b32 v255, s91, 11
	v_writelane_b32 v255, s92, 12
	v_writelane_b32 v255, s93, 13
	v_writelane_b32 v255, s94, 14
	v_writelane_b32 v255, s95, 15
	v_and_b32_e32 v207, 31, v227
	v_lshlrev_b32_e32 v200, 4, v207
	v_lshrrev_b32_e32 v201, 5, v227
	v_lshlrev_b32_e32 v202, 2, v207
	v_and_b32_e32 v203, 64, v202
	v_add_u32_e32 v203, v203, v202
	v_lshlrev_b32_e32 v204, 5, v201
	v_readlane_b32 s8, v253, 36
	v_readlane_b32 s9, v253, 37
	v_readlane_b32 s10, v253, 34
	v_readlane_b32 s11, v253, 35
	v_readlane_b32 s12, v253, 16
	v_readlane_b32 s13, v253, 17
	v_readlane_b32 s14, v253, 18
	v_readlane_b32 s15, v253, 19
	v_readlane_b32 s16, v253, 20
	v_readlane_b32 s17, v253, 21
	v_readlane_b32 s18, v253, 22
	v_readlane_b32 s19, v253, 23
	v_readfirstlane_b32 s66, v226
	s_lshr_b32 s66, s66, 6
	s_add_i32 s67, s2, 0xffffff80
	s_lshl_b32 s67, s67, 3
	s_add_i32 s66, s66, s67
	s_addk_i32 s66, 0xc00
	s_add_i32 s68, s66, 0x400
	s_add_i32 s67, s66, 0x800
	s_cmpk_ge_i32 s66, 0xc00
	s_cselect_b32 s0, 1, 0
	s_mul_i32 s1, s0, 0xc00
	s_sub_i32 s1, s66, s1
	s_mul_i32 s4, s0, 0x1800000
	s_add_u32 s70, s64, s4
	s_addc_u32 s71, s65, 0
	s_lshl_b32 s69, s0, 12
	s_cmpk_lt_i32 s1, 0x300
	s_cbranch_scc1 .Lw1_in_1
	s_cmpk_lt_i32 s1, 0x400
	s_cbranch_scc1 .Lw1_out_1
	s_cmpk_lt_i32 s1, 0x800
	s_cbranch_scc1 .Lw1_up_1
	s_sub_i32 s1, s1, 0x800
	s_and_b32 s75, s1, 1
	s_lshr_b32 s1, s1, 1
	s_lshr_b32 s72, s1, 3
	s_and_b32 s73, s1, 7
	s_lshl_b32 s72, s72, 1
	s_or_b32 s72, s72, s75
	s_movk_i32 s74, 0x400
	s_mul_i32 s4, s0, 0x1000000
	s_add_u32 s76, s18, s4
	s_addc_u32 s77, s19, 0
	s_mov_b32 s4, 0x1000000
	s_lshl_b32 s5, s73, 7
	s_movk_i32 s27, 0xd00
	s_branch .Lw1_join_1

.Lw1_join_1:
	s_mul_i32 s0, s72, s74
	s_lshl_b32 s0, s0, 5
	s_lshl_b32 s1, s73, 7
	s_add_i32 s0, s0, s1
	s_lshl_b32 s0, s0, 2
	s_add_u32 s20, s76, s0
	s_addc_u32 s21, s77, 0
	s_lshl_b32 s26, s74, 2
	s_lshr_b32 s0, s27, 8
	s_lshl_b32 s0, s5, s0
	s_add_i32 s0, s0, s4
	s_lshl_b32 s1, s72, 6
	s_add_i32 s0, s0, s1
	s_add_u32 s22, s70, s0
	s_addc_u32 s23, s71, 0
	s_lshl_b32 s1, s72, 7
	s_add_u32 s24, s24, s1
	s_addc_u32 s25, s25, 0
	s_lshl_b32 s0, s26, 4
	v_mad_u32_u24 v205, v201, s0, v200
	global_load_dwordx4 v[8:11], v205, s[20:21] nt
	s_add_u32 s20, s20, s26
	s_addc_u32 s21, s21, 0
	global_load_dwordx4 v[12:15], v205, s[20:21] nt
	s_add_u32 s20, s20, s26
	s_addc_u32 s21, s21, 0
	global_load_dwordx4 v[16:19], v205, s[20:21] nt
	s_add_u32 s20, s20, s26
	s_addc_u32 s21, s21, 0
	global_load_dwordx4 v[20:23], v205, s[20:21] nt
	s_add_u32 s20, s20, s26
	s_addc_u32 s21, s21, 0
	global_load_dwordx4 v[24:27], v205, s[20:21] nt
	s_add_u32 s20, s20, s26
	s_addc_u32 s21, s21, 0
	global_load_dwordx4 v[28:31], v205, s[20:21] nt
	s_add_u32 s20, s20, s26
	s_addc_u32 s21, s21, 0
	global_load_dwordx4 v[32:35], v205, s[20:21] nt
	s_add_u32 s20, s20, s26
	s_addc_u32 s21, s21, 0
	global_load_dwordx4 v[36:39], v205, s[20:21] nt
	s_add_u32 s20, s20, s26
	s_addc_u32 s21, s21, 0
	global_load_dwordx4 v[40:43], v205, s[20:21] nt
	s_add_u32 s20, s20, s26
	s_addc_u32 s21, s21, 0
	global_load_dwordx4 v[44:47], v205, s[20:21] nt
	s_add_u32 s20, s20, s26
	s_addc_u32 s21, s21, 0
	global_load_dwordx4 v[48:51], v205, s[20:21] nt
	s_add_u32 s20, s20, s26
	s_addc_u32 s21, s21, 0
	global_load_dwordx4 v[52:55], v205, s[20:21] nt
	s_add_u32 s20, s20, s26
	s_addc_u32 s21, s21, 0
	global_load_dwordx4 v[56:59], v205, s[20:21] nt
	s_add_u32 s20, s20, s26
	s_addc_u32 s21, s21, 0
	global_load_dwordx4 v[60:63], v205, s[20:21] nt
	s_add_u32 s20, s20, s26
	s_addc_u32 s21, s21, 0
	global_load_dwordx4 v[64:67], v205, s[20:21] nt
	s_add_u32 s20, s20, s26
	s_addc_u32 s21, s21, 0
	global_load_dwordx4 v[68:71], v205, s[20:21] nt
	s_cmpk_ge_i32 s68, 0xc00
	s_cselect_b32 s0, 1, 0
	s_mul_i32 s1, s0, 0xc00
	s_sub_i32 s1, s68, s1
	s_mul_i32 s4, s0, 0x1800000
	s_add_u32 s70, s64, s4
	s_addc_u32 s71, s65, 0
	s_lshl_b32 s69, s0, 12
	s_cmpk_lt_i32 s1, 0x300
	s_cbranch_scc1 .Lw1_in_2
	s_cmpk_lt_i32 s1, 0x400
	s_cbranch_scc1 .Lw1_out_2
	s_cmpk_lt_i32 s1, 0x800
	s_cbranch_scc1 .Lw1_up_2
	s_sub_i32 s1, s1, 0x800
	s_and_b32 s75, s1, 1
	s_lshr_b32 s1, s1, 1
	s_lshr_b32 s72, s1, 3
	s_and_b32 s73, s1, 7
	s_lshl_b32 s72, s72, 1
	s_or_b32 s72, s72, s75
	s_movk_i32 s74, 0x400
	s_mul_i32 s4, s0, 0x1000000
	s_add_u32 s76, s18, s4
	s_addc_u32 s77, s19, 0
	s_mov_b32 s4, 0x1000000
	s_lshl_b32 s5, s73, 7
	s_movk_i32 s35, 0xd00
	s_branch .Lw1_join_2

.Lw1_join_2:
	s_mul_i32 s0, s72, s74
	s_lshl_b32 s0, s0, 5
	s_lshl_b32 s1, s73, 7
	s_add_i32 s0, s0, s1
	s_lshl_b32 s0, s0, 2
	s_add_u32 s28, s76, s0
	s_addc_u32 s29, s77, 0
	s_lshl_b32 s34, s74, 2
	s_lshr_b32 s0, s35, 8
	s_lshl_b32 s0, s5, s0
	s_add_i32 s0, s0, s4
	s_lshl_b32 s1, s72, 6
	s_add_i32 s0, s0, s1
	s_add_u32 s30, s70, s0
	s_addc_u32 s31, s71, 0
	s_lshl_b32 s1, s72, 7
	s_add_u32 s32, s32, s1
	s_addc_u32 s33, s33, 0
	s_lshl_b32 s0, s34, 4
	v_mad_u32_u24 v205, v201, s0, v200
	global_load_dwordx4 v[72:75], v205, s[28:29] nt
	s_add_u32 s28, s28, s34
	s_addc_u32 s29, s29, 0
	global_load_dwordx4 v[76:79], v205, s[28:29] nt
	s_add_u32 s28, s28, s34
	s_addc_u32 s29, s29, 0
	global_load_dwordx4 v[80:83], v205, s[28:29] nt
	s_add_u32 s28, s28, s34
	s_addc_u32 s29, s29, 0
	global_load_dwordx4 v[84:87], v205, s[28:29] nt
	s_add_u32 s28, s28, s34
	s_addc_u32 s29, s29, 0
	global_load_dwordx4 v[88:91], v205, s[28:29] nt
	s_add_u32 s28, s28, s34
	s_addc_u32 s29, s29, 0
	global_load_dwordx4 v[92:95], v205, s[28:29] nt
	s_add_u32 s28, s28, s34
	s_addc_u32 s29, s29, 0
	global_load_dwordx4 v[96:99], v205, s[28:29] nt
	s_add_u32 s28, s28, s34
	s_addc_u32 s29, s29, 0
	global_load_dwordx4 v[100:103], v205, s[28:29] nt
	s_add_u32 s28, s28, s34
	s_addc_u32 s29, s29, 0
	global_load_dwordx4 v[104:107], v205, s[28:29] nt
	s_add_u32 s28, s28, s34
	s_addc_u32 s29, s29, 0
	global_load_dwordx4 v[108:111], v205, s[28:29] nt
	s_add_u32 s28, s28, s34
	s_addc_u32 s29, s29, 0
	global_load_dwordx4 v[112:115], v205, s[28:29] nt
	s_add_u32 s28, s28, s34
	s_addc_u32 s29, s29, 0
	global_load_dwordx4 v[116:119], v205, s[28:29] nt
	s_add_u32 s28, s28, s34
	s_addc_u32 s29, s29, 0
	global_load_dwordx4 v[120:123], v205, s[28:29] nt
	s_add_u32 s28, s28, s34
	s_addc_u32 s29, s29, 0
	global_load_dwordx4 v[124:127], v205, s[28:29] nt
	s_add_u32 s28, s28, s34
	s_addc_u32 s29, s29, 0
	global_load_dwordx4 v[128:131], v205, s[28:29] nt
	s_add_u32 s28, s28, s34
	s_addc_u32 s29, s29, 0
	global_load_dwordx4 v[132:135], v205, s[28:29] nt
	s_cmpk_ge_i32 s67, 0xc00
	s_cselect_b32 s0, 1, 0
	s_mul_i32 s1, s0, 0xc00
	s_sub_i32 s1, s67, s1
	s_mul_i32 s4, s0, 0x1800000
	s_add_u32 s70, s64, s4
	s_addc_u32 s71, s65, 0
	s_lshl_b32 s69, s0, 12
	s_cmpk_lt_i32 s1, 0x300
	s_cbranch_scc1 .Lw1_in_3
	s_cmpk_lt_i32 s1, 0x400
	s_cbranch_scc1 .Lw1_out_3
	s_cmpk_lt_i32 s1, 0x800
	s_cbranch_scc1 .Lw1_up_3
	s_sub_i32 s1, s1, 0x800
	s_and_b32 s75, s1, 1
	s_lshr_b32 s1, s1, 1
	s_lshr_b32 s72, s1, 3
	s_and_b32 s73, s1, 7
	s_lshl_b32 s72, s72, 1
	s_or_b32 s72, s72, s75
	s_movk_i32 s74, 0x400
	s_mul_i32 s4, s0, 0x1000000
	s_add_u32 s76, s18, s4
	s_addc_u32 s77, s19, 0
	s_mov_b32 s4, 0x1000000
	s_lshl_b32 s5, s73, 7
	s_movk_i32 s47, 0xd00
	s_branch .Lw1_join_3
